# step barrier: the last-arriving XCD leader bumps every XCD's release generation itself right after the top generation, leaders no longer relay it (one polling hop removed from the release chain)
# speedup vs baseline: 1.0111x; 1.0111x over previous
; __device__ __forceinline__ unsigned xb_ld(unsigned* p)              { return __hip_atomic_load(p, __ATOMIC_RELAXED, __HIP_MEMORY_SCOPE_AGENT); }
; __device__ __forceinline__ unsigned xb_add(unsigned* p, unsigned v) { return __hip_atomic_fetch_add(p, v, __ATOMIC_RELAXED, __HIP_MEMORY_SCOPE_AGENT); }
; #define XB_SPIN(cond, bar) do { unsigned _sp = 0; while (cond) { __builtin_amdgcn_s_sleep(1); \
;     if ((++_sp & 255u) == 0u) { if (xb_ld(&(bar)[XB_TMO])) break; if (_sp > XB_SPIN_CAP) { atomicAdd(&(bar)[XB_TMO], 1u); break; } } } } while (0)
; __device__ __forceinline__ void xcd_barrier(const XcdBarrier& b) {
;     ...
;         if (old + 1u == (gen + 1u) * nloc) {
;             __builtin_amdgcn_fence(__ATOMIC_RELEASE, "agent");
;             asm volatile("s_waitcnt vmcnt(0)" ::: "memory");
;             const unsigned og = xb_add(&bar[XB_TOP], 1u);
;             const unsigned tg = og / nx;
;             if (og + 1u == (tg + 1u) * nx) xb_add(&bar[XB_TOPGEN], 1u);
;             else XB_SPIN(xb_ld(&bar[XB_TOPGEN]) == tg, bar);
;             __builtin_amdgcn_fence(__ATOMIC_ACQUIRE, "agent");
;             xb_add(&bar[XB_XGEN(b.x)], 1u);
;             asm volatile("s_waitcnt vmcnt(0)" ::: "memory");
.LBB0_106:
	s_or_b64 exec, exec, s[2:3]
	buffer_inv sc1
	s_waitcnt vmcnt(0)

; __device__ __forceinline__ unsigned xb_ld(unsigned* p)              { return __hip_atomic_load(p, __ATOMIC_RELAXED, __HIP_MEMORY_SCOPE_AGENT); }
; __device__ __forceinline__ unsigned xb_add(unsigned* p, unsigned v) { return __hip_atomic_fetch_add(p, v, __ATOMIC_RELAXED, __HIP_MEMORY_SCOPE_AGENT); }
; #define XB_SPIN(cond, bar) do { unsigned _sp = 0; while (cond) { __builtin_amdgcn_s_sleep(1); \
;     if ((++_sp & 255u) == 0u) { if (xb_ld(&(bar)[XB_TMO])) break; if (_sp > XB_SPIN_CAP) { atomicAdd(&(bar)[XB_TMO], 1u); break; } } } } while (0)
; __device__ __forceinline__ void xcd_barrier(const XcdBarrier& b) {
;     ...
;             const unsigned og = xb_add(&bar[XB_TOP], 1u);
;             const unsigned tg = og / nx;
;             if (og + 1u == (tg + 1u) * nx) xb_add(&bar[XB_TOPGEN], 1u);
;             else XB_SPIN(xb_ld(&bar[XB_TOPGEN]) == tg, bar);
;             __builtin_amdgcn_fence(__ATOMIC_ACQUIRE, "agent");
;             xb_add(&bar[XB_XGEN(b.x)], 1u);
.LBB0_841:
	flat_atomic_add v[2:3], v243
	v_mov_b32_e32 v4, 0x2400
	global_atomic_add v4, v243, s[36:37]
	global_atomic_add v4, v243, s[36:37] offset:256
	global_atomic_add v4, v243, s[36:37] offset:512
	global_atomic_add v4, v243, s[36:37] offset:768
	global_atomic_add v4, v243, s[36:37] offset:1024
	global_atomic_add v4, v243, s[36:37] offset:1280
	global_atomic_add v4, v243, s[36:37] offset:1536
	global_atomic_add v4, v243, s[36:37] offset:1792
	global_atomic_add v4, v243, s[36:37] offset:2048
	global_atomic_add v4, v243, s[36:37] offset:2304
	global_atomic_add v4, v243, s[36:37] offset:2560
	global_atomic_add v4, v243, s[36:37] offset:2816
	global_atomic_add v4, v243, s[36:37] offset:3072
	global_atomic_add v4, v243, s[36:37] offset:3328
	global_atomic_add v4, v243, s[36:37] offset:3584
	global_atomic_add v4, v243, s[36:37] offset:3840
	s_getpc_b64 s[98:99]
